# index unit key-tile loop: 3 rotating key-fragment buffers, loads 3 tiles ahead (no same-iteration wait+copy)
# baseline (speedup 1.0000x reference)
; #define LAS __attribute__((address_space(3)))
;     template <class T> __device__ __forceinline__ T* w(size_t off) const { return (T*)(pp->ws + off); }
; template <class T> __device__ __forceinline__ LAS T* opq(LAS T* p) { asm volatile("" : "+v"(p)); return p; }
; __device__ __forceinline__ unsigned ordkey(float f) { const unsigned u = __float_as_uint(f); return u ^ ((u >> 31) ? 0xFFFFFFFFu : 0x80000000u); }
; __device__ __forceinline__ void dsa_index_unit(const Ctx& c, int l, int b, int qb) {
;     ...
;         const int tq = qb * 32 + 2 * p + hf;
;         bf16x8 Af[4];
;         { const bf16* qp = QI + (size_t)(r0 + 2 * p + ((n >> 2) & 1)) * 1024 + ((n & 3) + 4 * (n >> 3)) * 64 + 8 * hf;
; #pragma unroll
;           for (int ks = 0; ks < 4; ++ks) Af[ks] = *(const bf16x8*)(qp + 16 * ks); }
;         float wq[16];
;         { const float* wp = c.w<float>(WS_WI) + (size_t)(r0 + 2 * p + hf) * 16;
; #pragma unroll
;           for (int i = 0; i < 4; ++i) { const f32x4 w4 = *(const f32x4*)(wp + 4 * i); wq[4 * i] = w4[0] * 0.03125f; wq[4 * i + 1] = w4[1] * 0.03125f; wq[4 * i + 2] = w4[2] * 0.03125f; wq[4 * i + 3] = w4[3] * 0.03125f; } }
;         LAS unsigned* sk = opq((LAS unsigned*)c.lds + c.wave * 4096);
;         bf16x8 Bc[4];
;         { const bf16* kp = KI + (size_t)n * 64 + 8 * hf;
; #pragma unroll
;           for (int ks = 0; ks < 4; ++ks) Bc[ks] = *(const bf16x8*)(kp + 16 * ks); }
; #pragma unroll 1
;         for (int kt = 0; kt <= qb; ++kt) {
;             bf16x8 Bn[4];
;             { const int kn = kt < qb ? kt + 1 : kt; const bf16* kp = KI + (size_t)(kn * 32 + n) * 64 + 8 * hf;
; #pragma unroll
;               for (int ks = 0; ks < 4; ++ks) Bn[ks] = *(const bf16x8*)(kp + 16 * ks); }
;             f32x16 acc;
; #pragma unroll
;             for (int v = 0; v < 16; ++v) acc[v] = 0.f;
; #pragma unroll
;             for (int ks = 0; ks < 4; ++ks) acc = __builtin_amdgcn_mfma_f32_32x32x16_bf16(Af[ks], Bc[ks], acc, 0, 0, 0);
;             float sc = 0.f;
; #pragma unroll
;             for (int v = 0; v < 16; ++v) sc += wq[v] * fmaxf(acc[v], 0.f);
;             if (kt == qb && n > (tq & 31)) sc = -INFINITY;
;             sk[kt * 64 + lane] = ordkey(sc);
; #pragma unroll
;             for (int ks = 0; ks < 4; ++ks) Bc[ks] = Bn[ks];
;         }
.LBB0_1106:
	s_xor_b64 s[0:1], s[0:1], -1
	v_writelane_b32 v250, s0, 8
	v_readlane_b32 s4, v253, 35
	v_readlane_b32 s5, v253, 36
	v_writelane_b32 v250, s1, 9
	v_readlane_b32 s0, v251, 49
	s_add_i32 s0, s19, s0
	s_add_i32 s2, s0, s22
	v_or_b32_e32 v0, s2, v86
	v_ashrrev_i32_e32 v1, 31, v0
	v_lshlrev_b64 v[0:1], 11, v[0:1]
	v_lshl_add_u64 v[0:1], v[68:69], 0, v[0:1]
	global_load_dwordx4 v[18:21], v[0:1], off
	global_load_dwordx4 v[22:25], v[0:1], off offset:32
	global_load_dwordx4 v[26:29], v[0:1], off offset:64
	global_load_dwordx4 v[30:33], v[0:1], off offset:96
	v_add_u32_e32 v0, s2, v63
	v_ashrrev_i32_e32 v1, 31, v0
	v_lshlrev_b64 v[0:1], 6, v[0:1]
	v_lshl_add_u64 v[12:13], s[4:5], 0, v[0:1]
	global_load_dwordx4 v[0:3], v[12:13], off offset:48
	global_load_dwordx4 v[4:7], v[12:13], off offset:32
	global_load_dwordx4 v[8:11], v[12:13], off offset:16
	s_nop 0
	global_load_dwordx4 v[12:15], v[12:13], off
	v_readlane_b32 s1, v251, 50
	s_waitcnt vmcnt(3)
	v_pk_mul_f32 v[82:83], v[0:1], s[68:69] op_sel_hi:[1,0]
	s_waitcnt vmcnt(2)
	v_pk_mul_f32 v[78:79], v[4:5], s[68:69] op_sel_hi:[1,0]
	v_mov_b32_e32 v4, s1
	v_pk_mul_f32 v[84:85], v[2:3], s[68:69] op_sel_hi:[1,0]
	global_load_dwordx4 v[46:49], v[72:73], off
	global_load_dwordx4 v[50:53], v[72:73], off offset:32
	global_load_dwordx4 v[54:57], v[72:73], off offset:64
	global_load_dwordx4 v[58:61], v[72:73], off offset:96
	s_mov_b32 s45, 1
	v_lshl_or_b32 v16, s45, 5, v65
	v_lshlrev_b64 v[112:113], 7, v[16:17]
	v_lshl_add_u64 v[112:113], v[70:71], 0, v[112:113]
	global_load_dwordx4 v[96:99], v[112:113], off
	global_load_dwordx4 v[100:103], v[112:113], off offset:32
	global_load_dwordx4 v[104:107], v[112:113], off offset:64
	global_load_dwordx4 v[108:111], v[112:113], off offset:96
	s_mov_b32 s45, 2
	v_lshl_or_b32 v16, s45, 5, v65
	v_lshlrev_b64 v[112:113], 7, v[16:17]
	v_lshl_add_u64 v[112:113], v[70:71], 0, v[112:113]
	global_load_dwordx4 v[164:167], v[112:113], off
	global_load_dwordx4 v[168:171], v[112:113], off offset:32
	global_load_dwordx4 v[172:175], v[112:113], off offset:64
	global_load_dwordx4 v[176:179], v[112:113], off offset:96
	v_add_u32_e32 v5, s0, v63
	v_and_b32_e32 v5, 31, v5
	v_lshl_add_u32 v67, v66, 2, v4
	s_waitcnt vmcnt(12)
	v_mul_f32_e32 v88, 0x3d000000, v12
	v_mul_f32_e32 v89, 0x3d000000, v13
	v_mul_f32_e32 v90, 0x3d000000, v14
	v_mul_f32_e32 v91, 0x3d000000, v15
	v_mul_f32_e32 v92, 0x3d000000, v8
	v_mul_f32_e32 v93, 0x3d000000, v9
	v_pk_mul_f32 v[76:77], v[10:11], s[68:69] op_sel_hi:[1,0]
	v_pk_mul_f32 v[80:81], v[6:7], s[68:69] op_sel_hi:[1,0]
	v_cmp_gt_u32_e32 vcc, v65, v5
	v_mov_b32_e32 v94, v67
	s_mov_b32 s0, 0
	s_mov_b32 s44, 0
.LBB0_1107:
.Lix0_step0:
	s_waitcnt vmcnt(8)
	v_mfma_f32_32x32x16_bf16 v[0:15], v[18:21], v[46:49], 0
	v_mfma_f32_32x32x16_bf16 v[0:15], v[22:25], v[50:53], v[0:15]
	v_mfma_f32_32x32x16_bf16 v[0:15], v[26:29], v[54:57], v[0:15]
	v_mfma_f32_32x32x16_bf16 v[0:15], v[30:33], v[58:61], v[0:15]
	s_add_i32 s45, s44, 3
	s_min_u32 s45, s45, s16
	v_lshl_or_b32 v16, s45, 5, v65
	v_lshlrev_b64 v[112:113], 7, v[16:17]
	v_lshl_add_u64 v[112:113], v[70:71], 0, v[112:113]
	global_load_dwordx4 v[46:49], v[112:113], off
	global_load_dwordx4 v[50:53], v[112:113], off offset:32
	global_load_dwordx4 v[54:57], v[112:113], off offset:64
	global_load_dwordx4 v[58:61], v[112:113], off offset:96
	s_cmp_eq_u32 s16, s44
	s_cselect_b64 s[0:1], -1, 0
	s_and_b64 s[0:1], s[0:1], vcc
	s_nop 7
	v_max_f32_e32 v0, v0, v0
	v_max_f32_e32 v0, 0, v0
	v_fma_f32 v16, v88, v0, 0
	v_max_f32_e32 v0, v1, v1
	v_max_f32_e32 v0, 0, v0
	v_fmac_f32_e32 v16, v89, v0
	v_max_f32_e32 v0, v2, v2
	v_max_f32_e32 v0, 0, v0
	v_fmac_f32_e32 v16, v90, v0
	v_max_f32_e32 v0, v3, v3
	v_max_f32_e32 v0, 0, v0
	v_fmac_f32_e32 v16, v91, v0
	v_max_f32_e32 v0, v4, v4
	v_max_f32_e32 v0, 0, v0
	v_fmac_f32_e32 v16, v92, v0
	v_max_f32_e32 v0, v5, v5
	v_max_f32_e32 v0, 0, v0
	v_fmac_f32_e32 v16, v93, v0
	v_max_f32_e32 v0, v6, v6
	v_max_f32_e32 v1, v7, v7
	v_max_f32_e32 v0, 0, v0
	v_max_f32_e32 v1, 0, v1
	v_pk_mul_f32 v[0:1], v[76:77], v[0:1]
	s_nop 0
	v_add_f32_e32 v0, v0, v16
	v_add_f32_e32 v2, v1, v0
	v_max_f32_e32 v0, v8, v8
	v_max_f32_e32 v1, v9, v9
	v_max_f32_e32 v0, 0, v0
	v_max_f32_e32 v1, 0, v1
	v_pk_mul_f32 v[0:1], v[78:79], v[0:1]
	s_nop 0
	v_add_f32_e32 v0, v0, v2
	v_add_f32_e32 v2, v1, v0
	v_max_f32_e32 v0, v10, v10
	v_max_f32_e32 v1, v11, v11
	v_max_f32_e32 v0, 0, v0
	v_max_f32_e32 v1, 0, v1
	v_pk_mul_f32 v[0:1], v[80:81], v[0:1]
	s_nop 0
	v_add_f32_e32 v0, v0, v2
	v_add_f32_e32 v2, v1, v0
	v_max_f32_e32 v0, v12, v12
	v_max_f32_e32 v1, v13, v13
	v_max_f32_e32 v0, 0, v0
	v_max_f32_e32 v1, 0, v1
	v_pk_mul_f32 v[0:1], v[82:83], v[0:1]
	s_nop 0
	v_add_f32_e32 v0, v0, v2
	v_add_f32_e32 v2, v1, v0
	v_max_f32_e32 v0, v14, v14
	v_max_f32_e32 v1, v15, v15
	v_max_f32_e32 v0, 0, v0
	v_max_f32_e32 v1, 0, v1
	v_pk_mul_f32 v[0:1], v[84:85], v[0:1]
	s_nop 0
	v_add_f32_e32 v0, v0, v2
	v_add_f32_e32 v0, v1, v0
	v_cndmask_b32_e64 v0, v0, v139, s[0:1]
	v_cmp_lt_i32_e64 s[0:1], -1, v0
	s_nop 1
	v_cndmask_b32_e64 v1, -1, v140, s[0:1]
	v_xor_b32_e32 v0, v1, v0
	ds_write_b32 v94, v0
	v_add_u32_e32 v94, 0x100, v94
	s_add_i32 s44, s44, 1
	s_cmp_eq_u32 s18, s44
	s_cbranch_scc1 .Lix0_done
; __device__ __forceinline__ unsigned ordkey(float f) { const unsigned u = __float_as_uint(f); return u ^ ((u >> 31) ? 0xFFFFFFFFu : 0x80000000u); }
; __device__ __forceinline__ void dsa_index_unit(const Ctx& c, int l, int b, int qb) {
;     ...
;         for (int kt = 0; kt <= qb; ++kt) {
;             bf16x8 Bn[4];
;             { const int kn = kt < qb ? kt + 1 : kt; const bf16* kp = KI + (size_t)(kn * 32 + n) * 64 + 8 * hf;
; #pragma unroll
;               for (int ks = 0; ks < 4; ++ks) Bn[ks] = *(const bf16x8*)(kp + 16 * ks); }
;             f32x16 acc;
; #pragma unroll
;             for (int v = 0; v < 16; ++v) acc[v] = 0.f;
; #pragma unroll
;             for (int ks = 0; ks < 4; ++ks) acc = __builtin_amdgcn_mfma_f32_32x32x16_bf16(Af[ks], Bc[ks], acc, 0, 0, 0);
;             float sc = 0.f;
; #pragma unroll
;             for (int v = 0; v < 16; ++v) sc += wq[v] * fmaxf(acc[v], 0.f);
;             if (kt == qb && n > (tq & 31)) sc = -INFINITY;
;             sk[kt * 64 + lane] = ordkey(sc);
; #pragma unroll
;             for (int ks = 0; ks < 4; ++ks) Bc[ks] = Bn[ks];
;         }
.Lix0_step1:
	s_waitcnt vmcnt(8)
	v_mfma_f32_32x32x16_bf16 v[0:15], v[18:21], v[96:99], 0
	v_mfma_f32_32x32x16_bf16 v[0:15], v[22:25], v[100:103], v[0:15]
	v_mfma_f32_32x32x16_bf16 v[0:15], v[26:29], v[104:107], v[0:15]
	v_mfma_f32_32x32x16_bf16 v[0:15], v[30:33], v[108:111], v[0:15]
	s_add_i32 s45, s44, 3
	s_min_u32 s45, s45, s16
	v_lshl_or_b32 v16, s45, 5, v65
	v_lshlrev_b64 v[112:113], 7, v[16:17]
	v_lshl_add_u64 v[112:113], v[70:71], 0, v[112:113]
	global_load_dwordx4 v[96:99], v[112:113], off
	global_load_dwordx4 v[100:103], v[112:113], off offset:32
	global_load_dwordx4 v[104:107], v[112:113], off offset:64
	global_load_dwordx4 v[108:111], v[112:113], off offset:96
	s_cmp_eq_u32 s16, s44
	s_cselect_b64 s[0:1], -1, 0
	s_and_b64 s[0:1], s[0:1], vcc
	s_nop 7
	v_max_f32_e32 v0, v0, v0
	v_max_f32_e32 v0, 0, v0
	v_fma_f32 v16, v88, v0, 0
	v_max_f32_e32 v0, v1, v1
	v_max_f32_e32 v0, 0, v0
	v_fmac_f32_e32 v16, v89, v0
	v_max_f32_e32 v0, v2, v2
	v_max_f32_e32 v0, 0, v0
	v_fmac_f32_e32 v16, v90, v0
	v_max_f32_e32 v0, v3, v3
	v_max_f32_e32 v0, 0, v0
	v_fmac_f32_e32 v16, v91, v0
	v_max_f32_e32 v0, v4, v4
	v_max_f32_e32 v0, 0, v0
	v_fmac_f32_e32 v16, v92, v0
	v_max_f32_e32 v0, v5, v5
	v_max_f32_e32 v0, 0, v0
	v_fmac_f32_e32 v16, v93, v0
	v_max_f32_e32 v0, v6, v6
	v_max_f32_e32 v1, v7, v7
	v_max_f32_e32 v0, 0, v0
	v_max_f32_e32 v1, 0, v1
	v_pk_mul_f32 v[0:1], v[76:77], v[0:1]
	s_nop 0
	v_add_f32_e32 v0, v0, v16
	v_add_f32_e32 v2, v1, v0
	v_max_f32_e32 v0, v8, v8
	v_max_f32_e32 v1, v9, v9
	v_max_f32_e32 v0, 0, v0
	v_max_f32_e32 v1, 0, v1
	v_pk_mul_f32 v[0:1], v[78:79], v[0:1]
	s_nop 0
	v_add_f32_e32 v0, v0, v2
	v_add_f32_e32 v2, v1, v0
	v_max_f32_e32 v0, v10, v10
	v_max_f32_e32 v1, v11, v11
	v_max_f32_e32 v0, 0, v0
	v_max_f32_e32 v1, 0, v1
	v_pk_mul_f32 v[0:1], v[80:81], v[0:1]
	s_nop 0
	v_add_f32_e32 v0, v0, v2
	v_add_f32_e32 v2, v1, v0
	v_max_f32_e32 v0, v12, v12
	v_max_f32_e32 v1, v13, v13
	v_max_f32_e32 v0, 0, v0
	v_max_f32_e32 v1, 0, v1
	v_pk_mul_f32 v[0:1], v[82:83], v[0:1]
	s_nop 0
	v_add_f32_e32 v0, v0, v2
	v_add_f32_e32 v2, v1, v0
	v_max_f32_e32 v0, v14, v14
	v_max_f32_e32 v1, v15, v15
	v_max_f32_e32 v0, 0, v0
	v_max_f32_e32 v1, 0, v1
	v_pk_mul_f32 v[0:1], v[84:85], v[0:1]
	s_nop 0
	v_add_f32_e32 v0, v0, v2
	v_add_f32_e32 v0, v1, v0
	v_cndmask_b32_e64 v0, v0, v139, s[0:1]
	v_cmp_lt_i32_e64 s[0:1], -1, v0
	s_nop 1
	v_cndmask_b32_e64 v1, -1, v140, s[0:1]
	v_xor_b32_e32 v0, v1, v0
	ds_write_b32 v94, v0
	v_add_u32_e32 v94, 0x100, v94
	s_add_i32 s44, s44, 1
	s_cmp_eq_u32 s18, s44
	s_cbranch_scc1 .Lix0_done
.Lix0_step2:
	s_waitcnt vmcnt(8)
	v_mfma_f32_32x32x16_bf16 v[0:15], v[18:21], v[164:167], 0
	v_mfma_f32_32x32x16_bf16 v[0:15], v[22:25], v[168:171], v[0:15]
	v_mfma_f32_32x32x16_bf16 v[0:15], v[26:29], v[172:175], v[0:15]
	v_mfma_f32_32x32x16_bf16 v[0:15], v[30:33], v[176:179], v[0:15]
	s_add_i32 s45, s44, 3
	s_min_u32 s45, s45, s16
	v_lshl_or_b32 v16, s45, 5, v65
	v_lshlrev_b64 v[112:113], 7, v[16:17]
	v_lshl_add_u64 v[112:113], v[70:71], 0, v[112:113]
	global_load_dwordx4 v[164:167], v[112:113], off
	global_load_dwordx4 v[168:171], v[112:113], off offset:32
	global_load_dwordx4 v[172:175], v[112:113], off offset:64
	global_load_dwordx4 v[176:179], v[112:113], off offset:96
	s_cmp_eq_u32 s16, s44
	s_cselect_b64 s[0:1], -1, 0
	s_and_b64 s[0:1], s[0:1], vcc
	s_nop 7
	v_max_f32_e32 v0, v0, v0
	v_max_f32_e32 v0, 0, v0
	v_fma_f32 v16, v88, v0, 0
	v_max_f32_e32 v0, v1, v1
	v_max_f32_e32 v0, 0, v0
	v_fmac_f32_e32 v16, v89, v0
	v_max_f32_e32 v0, v2, v2
	v_max_f32_e32 v0, 0, v0
	v_fmac_f32_e32 v16, v90, v0
	v_max_f32_e32 v0, v3, v3
	v_max_f32_e32 v0, 0, v0
	v_fmac_f32_e32 v16, v91, v0
	v_max_f32_e32 v0, v4, v4
	v_max_f32_e32 v0, 0, v0
	v_fmac_f32_e32 v16, v92, v0
	v_max_f32_e32 v0, v5, v5
	v_max_f32_e32 v0, 0, v0
	v_fmac_f32_e32 v16, v93, v0
	v_max_f32_e32 v0, v6, v6
	v_max_f32_e32 v1, v7, v7
	v_max_f32_e32 v0, 0, v0
	v_max_f32_e32 v1, 0, v1
	v_pk_mul_f32 v[0:1], v[76:77], v[0:1]
	s_nop 0
	v_add_f32_e32 v0, v0, v16
	v_add_f32_e32 v2, v1, v0
	v_max_f32_e32 v0, v8, v8
	v_max_f32_e32 v1, v9, v9
	v_max_f32_e32 v0, 0, v0
	v_max_f32_e32 v1, 0, v1
	v_pk_mul_f32 v[0:1], v[78:79], v[0:1]
	s_nop 0
	v_add_f32_e32 v0, v0, v2
	v_add_f32_e32 v2, v1, v0
	v_max_f32_e32 v0, v10, v10
	v_max_f32_e32 v1, v11, v11
	v_max_f32_e32 v0, 0, v0
	v_max_f32_e32 v1, 0, v1
	v_pk_mul_f32 v[0:1], v[80:81], v[0:1]
	s_nop 0
	v_add_f32_e32 v0, v0, v2
	v_add_f32_e32 v2, v1, v0
	v_max_f32_e32 v0, v12, v12
	v_max_f32_e32 v1, v13, v13
	v_max_f32_e32 v0, 0, v0
	v_max_f32_e32 v1, 0, v1
	v_pk_mul_f32 v[0:1], v[82:83], v[0:1]
	s_nop 0
	v_add_f32_e32 v0, v0, v2
	v_add_f32_e32 v2, v1, v0
	v_max_f32_e32 v0, v14, v14
	v_max_f32_e32 v1, v15, v15
	v_max_f32_e32 v0, 0, v0
	v_max_f32_e32 v1, 0, v1
	v_pk_mul_f32 v[0:1], v[84:85], v[0:1]
	s_nop 0
	v_add_f32_e32 v0, v0, v2
	v_add_f32_e32 v0, v1, v0
	v_cndmask_b32_e64 v0, v0, v139, s[0:1]
	v_cmp_lt_i32_e64 s[0:1], -1, v0
	s_nop 1
	v_cndmask_b32_e64 v1, -1, v140, s[0:1]
	v_xor_b32_e32 v0, v1, v0
	ds_write_b32 v94, v0
	v_add_u32_e32 v94, 0x100, v94
	s_add_i32 s44, s44, 1
	s_cmp_eq_u32 s18, s44
	s_cbranch_scc1 .Lix0_done
	s_branch .Lix0_step0
; __device__ __forceinline__ void dsa_index_unit(const Ctx& c, int l, int b, int qb) {
;     ...
;         unsigned key[64];
; #pragma unroll
;         for (int kt = 0; kt < 64; ++kt) { const unsigned kv = sk[kt * 64 + lane]; key[kt] = (kt <= qb) ? kv : 0u; }
.Lix0_done:
	s_waitcnt vmcnt(0)
	ds_read2st64_b32 v[8:9], v67 offset1:1
	ds_read2st64_b32 v[6:7], v67 offset0:2 offset1:3
	ds_read2st64_b32 v[4:5], v67 offset0:4 offset1:5
	ds_read2st64_b32 v[2:3], v67 offset0:6 offset1:7
	ds_read2st64_b32 v[0:1], v67 offset0:8 offset1:9
	ds_read2st64_b32 v[10:11], v67 offset0:10 offset1:11
	ds_read2st64_b32 v[102:103], v67 offset0:62 offset1:63
	v_readlane_b32 s0, v250, 22
	v_readlane_b32 s1, v250, 23
	s_mov_b64 s[20:21], s[90:91]
	s_waitcnt lgkmcnt(2)
	v_cndmask_b32_e64 v101, v1, 0, s[0:1]
	v_readlane_b32 s0, v250, 16
	v_readlane_b32 s1, v250, 17
	s_waitcnt lgkmcnt(1)
	s_nop 0
	v_cndmask_b32_e64 v99, v10, 0, s[0:1]
	v_readlane_b32 s0, v250, 18
	v_readlane_b32 s1, v250, 19
	s_nop 1
	v_cndmask_b32_e64 v98, v11, 0, s[0:1]
	ds_read2st64_b32 v[10:11], v67 offset0:12 offset1:13
	v_readlane_b32 s0, v250, 26
	v_readlane_b32 s1, v250, 27
	s_waitcnt lgkmcnt(0)
	s_nop 0
	v_cndmask_b32_e64 v96, v10, 0, s[0:1]
	v_readlane_b32 s0, v250, 28
	v_readlane_b32 s1, v250, 29
	s_nop 1
	v_cndmask_b32_e64 v95, v11, 0, s[0:1]
	ds_read2st64_b32 v[10:11], v67 offset0:14 offset1:15
	v_readlane_b32 s0, v250, 30
	v_readlane_b32 s1, v250, 31
	s_waitcnt lgkmcnt(0)
	s_nop 0
	v_cndmask_b32_e64 v93, v10, 0, s[0:1]
	v_readlane_b32 s0, v250, 24
	v_readlane_b32 s1, v250, 25
	s_nop 1
	v_cndmask_b32_e64 v92, v11, 0, s[0:1]
	ds_read2st64_b32 v[10:11], v67 offset0:16 offset1:17
	v_readlane_b32 s0, v250, 40
	v_readlane_b32 s1, v250, 41
	s_waitcnt lgkmcnt(0)
	s_nop 0
	v_cndmask_b32_e64 v90, v10, 0, s[0:1]
	v_readlane_b32 s0, v250, 32
	v_readlane_b32 s1, v250, 33
	s_nop 1
	v_cndmask_b32_e64 v89, v11, 0, s[0:1]
	ds_read2st64_b32 v[10:11], v67 offset0:18 offset1:19
	v_readlane_b32 s0, v250, 10
	v_readlane_b32 s1, v250, 11
	s_waitcnt lgkmcnt(0)
	s_nop 0
	v_cndmask_b32_e64 v85, v10, 0, s[0:1]
	v_readlane_b32 s0, v250, 14
	v_readlane_b32 s1, v250, 15
	s_nop 1
	v_cndmask_b32_e64 v84, v11, 0, s[0:1]
	ds_read2st64_b32 v[10:11], v67 offset0:20 offset1:21
	v_readlane_b32 s0, v250, 34
	v_readlane_b32 s1, v250, 35
	s_waitcnt lgkmcnt(0)
	s_nop 0
	v_cndmask_b32_e64 v83, v10, 0, s[0:1]
	v_readlane_b32 s0, v250, 36
	v_readlane_b32 s1, v250, 37
	s_nop 1
	v_cndmask_b32_e64 v81, v11, 0, s[0:1]
	ds_read2st64_b32 v[10:11], v67 offset0:22 offset1:23
	v_readlane_b32 s0, v250, 38
	v_readlane_b32 s1, v250, 39
	s_waitcnt lgkmcnt(0)
	s_nop 0
	v_cndmask_b32_e64 v80, v10, 0, s[0:1]
	v_readlane_b32 s0, v252, 17
	v_readlane_b32 s1, v252, 18
	s_nop 1
	v_cndmask_b32_e64 v78, v11, 0, s[0:1]
	ds_read2st64_b32 v[10:11], v67 offset0:24 offset1:25
	v_readlane_b32 s0, v252, 19
	v_readlane_b32 s1, v252, 20
	s_waitcnt lgkmcnt(0)
	s_nop 0
	v_cndmask_b32_e64 v77, v10, 0, s[0:1]
	v_readlane_b32 s0, v252, 21
	v_readlane_b32 s1, v252, 22
	s_nop 1
	v_cndmask_b32_e64 v76, v11, 0, s[0:1]
	ds_read2st64_b32 v[10:11], v67 offset0:26 offset1:27
	v_readlane_b32 s0, v252, 23
	v_readlane_b32 s1, v252, 24
	s_waitcnt lgkmcnt(0)
	s_nop 0
	v_cndmask_b32_e64 v61, v10, 0, s[0:1]
	v_readlane_b32 s0, v252, 25
	v_readlane_b32 s1, v252, 26
	s_nop 1
	v_cndmask_b32_e64 v60, v11, 0, s[0:1]
	ds_read2st64_b32 v[10:11], v67 offset0:28 offset1:29
	v_readlane_b32 s0, v252, 27
	v_readlane_b32 s1, v252, 28
	s_waitcnt lgkmcnt(0)
	s_nop 0
	v_cndmask_b32_e64 v58, v10, 0, s[0:1]
	v_readlane_b32 s0, v252, 29
	v_readlane_b32 s1, v252, 30
	s_nop 1
	v_cndmask_b32_e64 v57, v11, 0, s[0:1]
	ds_read2st64_b32 v[10:11], v67 offset0:30 offset1:31
	v_readlane_b32 s0, v252, 31
	v_readlane_b32 s1, v252, 32
	s_waitcnt lgkmcnt(0)
	s_nop 0
	v_cndmask_b32_e64 v55, v10, 0, s[0:1]
	v_readlane_b32 s0, v252, 33
	v_readlane_b32 s1, v252, 34
	s_nop 1
	v_cndmask_b32_e64 v54, v11, 0, s[0:1]
	ds_read2st64_b32 v[10:11], v67 offset0:32 offset1:33
	v_readlane_b32 s0, v252, 35
	v_readlane_b32 s1, v252, 36
	s_waitcnt lgkmcnt(0)
	s_nop 0
	v_cndmask_b32_e64 v52, v10, 0, s[0:1]
	v_readlane_b32 s0, v252, 37
	v_readlane_b32 s1, v252, 38
	s_nop 1
	v_cndmask_b32_e64 v51, v11, 0, s[0:1]
	ds_read2st64_b32 v[10:11], v67 offset0:34 offset1:35
	v_readlane_b32 s0, v252, 39
	v_readlane_b32 s1, v252, 40
	s_waitcnt lgkmcnt(0)
; __device__ __forceinline__ void dsa_index_unit(const Ctx& c, int l, int b, int qb) {
;     ...
;         unsigned key[64];
; #pragma unroll
;         for (int kt = 0; kt < 64; ++kt) { const unsigned kv = sk[kt * 64 + lane]; key[kt] = (kt <= qb) ? kv : 0u; }
;         unsigned T = 0u;
; #pragma unroll 1
	s_nop 0
	v_cndmask_b32_e64 v49, v10, 0, s[0:1]
	v_readlane_b32 s0, v252, 41
	v_readlane_b32 s1, v252, 42
	s_nop 1
	v_cndmask_b32_e64 v48, v11, 0, s[0:1]
	ds_read2st64_b32 v[10:11], v67 offset0:36 offset1:37
	v_readlane_b32 s0, v252, 43
	v_readlane_b32 s1, v252, 44
	s_waitcnt lgkmcnt(0)
	s_nop 0
	v_cndmask_b32_e64 v46, v10, 0, s[0:1]
	v_readlane_b32 s0, v252, 45
	v_readlane_b32 s1, v252, 46
	s_nop 1
	v_cndmask_b32_e64 v45, v11, 0, s[0:1]
	ds_read2st64_b32 v[10:11], v67 offset0:38 offset1:39
	v_readlane_b32 s0, v252, 47
	v_readlane_b32 s1, v252, 48
	s_waitcnt lgkmcnt(0)
	s_nop 0
	v_cndmask_b32_e64 v43, v10, 0, s[0:1]
	v_readlane_b32 s0, v252, 49
	v_readlane_b32 s1, v252, 50
	s_nop 1
	v_cndmask_b32_e64 v42, v11, 0, s[0:1]
	ds_read2st64_b32 v[10:11], v67 offset0:40 offset1:41
	v_readlane_b32 s0, v252, 51
	v_readlane_b32 s1, v252, 52
	s_waitcnt lgkmcnt(0)
	s_nop 0
	v_cndmask_b32_e64 v40, v10, 0, s[0:1]
	v_readlane_b32 s0, v252, 53
	v_readlane_b32 s1, v252, 54
	s_nop 1
	v_cndmask_b32_e64 v39, v11, 0, s[0:1]
	ds_read2st64_b32 v[10:11], v67 offset0:42 offset1:43
	v_readlane_b32 s0, v252, 55
	v_readlane_b32 s1, v252, 56
	s_waitcnt lgkmcnt(0)
	s_nop 0
	v_cndmask_b32_e64 v38, v10, 0, s[0:1]
	v_readlane_b32 s0, v252, 57
	v_readlane_b32 s1, v252, 58
	s_nop 1
	v_cndmask_b32_e64 v36, v11, 0, s[0:1]
	ds_read2st64_b32 v[10:11], v67 offset0:44 offset1:45
	v_readlane_b32 s0, v252, 59
	v_readlane_b32 s1, v252, 60
	s_waitcnt lgkmcnt(0)
	s_nop 0
	v_cndmask_b32_e64 v35, v10, 0, s[0:1]
	v_readlane_b32 s0, v252, 61
	v_readlane_b32 s1, v252, 62
	s_nop 1
	v_cndmask_b32_e64 v33, v11, 0, s[0:1]
	ds_read2st64_b32 v[10:11], v67 offset0:46 offset1:47
	v_readlane_b32 s0, v252, 63
	v_readlane_b32 s1, v253, 0
	s_waitcnt lgkmcnt(0)
	s_nop 0
	v_cndmask_b32_e64 v32, v10, 0, s[0:1]
	v_readlane_b32 s0, v253, 1
	v_readlane_b32 s1, v253, 2
	s_nop 1
	v_cndmask_b32_e64 v30, v11, 0, s[0:1]
	ds_read2st64_b32 v[10:11], v67 offset0:48 offset1:49
	v_readlane_b32 s0, v253, 3
	v_readlane_b32 s1, v253, 4
	s_waitcnt lgkmcnt(0)
	s_nop 0
	v_cndmask_b32_e64 v29, v10, 0, s[0:1]
	v_readlane_b32 s0, v253, 5
	v_readlane_b32 s1, v253, 6
	s_nop 1
	v_cndmask_b32_e64 v27, v11, 0, s[0:1]
	ds_read2st64_b32 v[10:11], v67 offset0:50 offset1:51
	v_readlane_b32 s0, v253, 7
	v_readlane_b32 s1, v253, 8
	s_waitcnt lgkmcnt(0)
	s_nop 0
	v_cndmask_b32_e64 v26, v10, 0, s[0:1]
	v_readlane_b32 s0, v253, 9
	v_readlane_b32 s1, v253, 10
	s_nop 1
	v_cndmask_b32_e64 v24, v11, 0, s[0:1]
	ds_read2st64_b32 v[10:11], v67 offset0:52 offset1:53
	v_readlane_b32 s0, v253, 11
	v_readlane_b32 s1, v253, 12
	s_waitcnt lgkmcnt(0)
	s_nop 0
	v_cndmask_b32_e64 v22, v10, 0, s[0:1]
	v_readlane_b32 s0, v253, 13
	v_readlane_b32 s1, v253, 14
	s_nop 1
	v_cndmask_b32_e64 v21, v11, 0, s[0:1]
	ds_read2st64_b32 v[10:11], v67 offset0:54 offset1:55
	v_readlane_b32 s0, v253, 15
	v_readlane_b32 s1, v253, 16
	s_waitcnt lgkmcnt(0)
	s_nop 0
	v_cndmask_b32_e64 v20, v10, 0, s[0:1]
	v_readlane_b32 s0, v253, 17
	v_readlane_b32 s1, v253, 18
	s_nop 1
	v_cndmask_b32_e64 v19, v11, 0, s[0:1]
	ds_read2st64_b32 v[10:11], v67 offset0:56 offset1:57
	v_readlane_b32 s0, v253, 19
	v_readlane_b32 s1, v253, 20
	s_waitcnt lgkmcnt(0)
	s_nop 0
	v_cndmask_b32_e64 v18, v10, 0, s[0:1]
	v_readlane_b32 s0, v253, 21
	v_readlane_b32 s1, v253, 22
	s_nop 1
	v_cndmask_b32_e64 v16, v11, 0, s[0:1]
	ds_read2st64_b32 v[10:11], v67 offset0:58 offset1:59
	v_readlane_b32 s0, v253, 23
	v_readlane_b32 s1, v253, 24
	s_waitcnt lgkmcnt(0)
	s_nop 0
	v_cndmask_b32_e64 v15, v10, 0, s[0:1]
	v_readlane_b32 s0, v253, 25
	v_readlane_b32 s1, v253, 26
	s_nop 1
	v_cndmask_b32_e64 v14, v11, 0, s[0:1]
	ds_read2st64_b32 v[10:11], v67 offset0:60 offset1:61
	v_readlane_b32 s0, v253, 27
	v_readlane_b32 s1, v253, 28
	s_waitcnt lgkmcnt(0)
	s_nop 0
	v_cndmask_b32_e64 v13, v10, 0, s[0:1]
	v_readlane_b32 s0, v253, 29
	v_readlane_b32 s1, v253, 30
	v_mov_b32_e32 v10, 0
	s_nop 0
	v_cndmask_b32_e64 v12, v11, 0, s[0:1]
	v_readlane_b32 s0, v253, 31
	v_readlane_b32 s1, v253, 32
	s_nop 1
	v_cndmask_b32_e64 v11, v102, 0, s[0:1]
	v_readlane_b32 s0, v253, 33
	v_readlane_b32 s1, v253, 34
	s_nop 1
	v_cndmask_b32_e64 v1, 0, v103, s[0:1]
	s_mov_b32 s0, 31

; #define LAS __attribute__((address_space(3)))
;     template <class T> __device__ __forceinline__ T* w(size_t off) const { return (T*)(pp->ws + off); }
; template <class T> __device__ __forceinline__ LAS T* opq(LAS T* p) { asm volatile("" : "+v"(p)); return p; }
; __device__ __forceinline__ unsigned ordkey(float f) { const unsigned u = __float_as_uint(f); return u ^ ((u >> 31) ? 0xFFFFFFFFu : 0x80000000u); }
; __device__ __forceinline__ void dsa_index_unit(const Ctx& c, int l, int b, int qb) {
;     ...
;         const int tq = qb * 32 + 2 * p + hf;
;         bf16x8 Af[4];
;         { const bf16* qp = QI + (size_t)(r0 + 2 * p + ((n >> 2) & 1)) * 1024 + ((n & 3) + 4 * (n >> 3)) * 64 + 8 * hf;
; #pragma unroll
;           for (int ks = 0; ks < 4; ++ks) Af[ks] = *(const bf16x8*)(qp + 16 * ks); }
;         float wq[16];
;         { const float* wp = c.w<float>(WS_WI) + (size_t)(r0 + 2 * p + hf) * 16;
; #pragma unroll
;           for (int i = 0; i < 4; ++i) { const f32x4 w4 = *(const f32x4*)(wp + 4 * i); wq[4 * i] = w4[0] * 0.03125f; wq[4 * i + 1] = w4[1] * 0.03125f; wq[4 * i + 2] = w4[2] * 0.03125f; wq[4 * i + 3] = w4[3] * 0.03125f; } }
;         LAS unsigned* sk = opq((LAS unsigned*)c.lds + c.wave * 4096);
;         bf16x8 Bc[4];
;         { const bf16* kp = KI + (size_t)n * 64 + 8 * hf;
; #pragma unroll
;           for (int ks = 0; ks < 4; ++ks) Bc[ks] = *(const bf16x8*)(kp + 16 * ks); }
; #pragma unroll 1
;         for (int kt = 0; kt <= qb; ++kt) {
;             bf16x8 Bn[4];
;             { const int kn = kt < qb ? kt + 1 : kt; const bf16* kp = KI + (size_t)(kn * 32 + n) * 64 + 8 * hf;
; #pragma unroll
;               for (int ks = 0; ks < 4; ++ks) Bn[ks] = *(const bf16x8*)(kp + 16 * ks); }
;             f32x16 acc;
; #pragma unroll
;             for (int v = 0; v < 16; ++v) acc[v] = 0.f;
; #pragma unroll
;             for (int ks = 0; ks < 4; ++ks) acc = __builtin_amdgcn_mfma_f32_32x32x16_bf16(Af[ks], Bc[ks], acc, 0, 0, 0);
;             float sc = 0.f;
; #pragma unroll
;             for (int v = 0; v < 16; ++v) sc += wq[v] * fmaxf(acc[v], 0.f);
;             if (kt == qb && n > (tq & 31)) sc = -INFINITY;
;             sk[kt * 64 + lane] = ordkey(sc);
; #pragma unroll
;             for (int ks = 0; ks < 4; ++ks) Bc[ks] = Bn[ks];
;         }
.LBB0_2629:
	s_xor_b64 s[0:1], s[0:1], -1
	v_writelane_b32 v250, s0, 8
	v_readlane_b32 s2, v253, 35
	v_readlane_b32 s3, v253, 36
	v_writelane_b32 v250, s1, 9
	v_readlane_b32 s0, v251, 49
	s_add_i32 s0, s19, s0
	s_add_i32 s16, s0, s11
	v_or_b32_e32 v0, s16, v86
	v_ashrrev_i32_e32 v1, 31, v0
	v_lshlrev_b64 v[0:1], 11, v[0:1]
	v_lshl_add_u64 v[0:1], v[68:69], 0, v[0:1]
	global_load_dwordx4 v[18:21], v[0:1], off
	global_load_dwordx4 v[22:25], v[0:1], off offset:32
	global_load_dwordx4 v[26:29], v[0:1], off offset:64
	global_load_dwordx4 v[30:33], v[0:1], off offset:96
	v_add_u32_e32 v0, s16, v63
	v_ashrrev_i32_e32 v1, 31, v0
	v_lshlrev_b64 v[0:1], 6, v[0:1]
	v_lshl_add_u64 v[12:13], s[2:3], 0, v[0:1]
	global_load_dwordx4 v[0:3], v[12:13], off offset:48
	global_load_dwordx4 v[4:7], v[12:13], off offset:32
	global_load_dwordx4 v[8:11], v[12:13], off offset:16
	s_nop 0
	global_load_dwordx4 v[12:15], v[12:13], off
	v_readlane_b32 s1, v251, 50
	s_waitcnt vmcnt(3)
	v_pk_mul_f32 v[82:83], v[0:1], s[68:69] op_sel_hi:[1,0]
	s_waitcnt vmcnt(2)
	v_pk_mul_f32 v[78:79], v[4:5], s[68:69] op_sel_hi:[1,0]
	v_mov_b32_e32 v4, s1
	v_pk_mul_f32 v[84:85], v[2:3], s[68:69] op_sel_hi:[1,0]
	global_load_dwordx4 v[46:49], v[72:73], off
	global_load_dwordx4 v[50:53], v[72:73], off offset:32
	global_load_dwordx4 v[54:57], v[72:73], off offset:64
	global_load_dwordx4 v[58:61], v[72:73], off offset:96
	s_mov_b32 s45, 1
	v_lshl_or_b32 v16, s45, 5, v65
	v_lshlrev_b64 v[112:113], 7, v[16:17]
	v_lshl_add_u64 v[112:113], v[70:71], 0, v[112:113]
	global_load_dwordx4 v[96:99], v[112:113], off
	global_load_dwordx4 v[100:103], v[112:113], off offset:32
	global_load_dwordx4 v[104:107], v[112:113], off offset:64
	global_load_dwordx4 v[108:111], v[112:113], off offset:96
	s_mov_b32 s45, 2
	v_lshl_or_b32 v16, s45, 5, v65
	v_lshlrev_b64 v[112:113], 7, v[16:17]
	v_lshl_add_u64 v[112:113], v[70:71], 0, v[112:113]
	global_load_dwordx4 v[164:167], v[112:113], off
	global_load_dwordx4 v[168:171], v[112:113], off offset:32
	global_load_dwordx4 v[172:175], v[112:113], off offset:64
	global_load_dwordx4 v[176:179], v[112:113], off offset:96
	v_add_u32_e32 v5, s0, v63
	v_and_b32_e32 v5, 31, v5
	v_lshl_add_u32 v67, v66, 2, v4
	s_waitcnt vmcnt(12)
	v_mul_f32_e32 v88, 0x3d000000, v12
	v_mul_f32_e32 v89, 0x3d000000, v13
	v_mul_f32_e32 v90, 0x3d000000, v14
	v_mul_f32_e32 v91, 0x3d000000, v15
	v_mul_f32_e32 v92, 0x3d000000, v8
	v_mul_f32_e32 v93, 0x3d000000, v9
	v_pk_mul_f32 v[76:77], v[10:11], s[68:69] op_sel_hi:[1,0]
	v_pk_mul_f32 v[80:81], v[6:7], s[68:69] op_sel_hi:[1,0]
	v_cmp_gt_u32_e32 vcc, v65, v5
	v_mov_b32_e32 v94, v67
	s_mov_b32 s0, 0
	s_mov_b32 s44, 0
.LBB0_2630:
.Lix1_step0:
	s_waitcnt vmcnt(8)
	v_mfma_f32_32x32x16_bf16 v[0:15], v[18:21], v[46:49], 0
	v_mfma_f32_32x32x16_bf16 v[0:15], v[22:25], v[50:53], v[0:15]
	v_mfma_f32_32x32x16_bf16 v[0:15], v[26:29], v[54:57], v[0:15]
	v_mfma_f32_32x32x16_bf16 v[0:15], v[30:33], v[58:61], v[0:15]
	s_add_i32 s45, s44, 3
	s_min_u32 s45, s45, s14
	v_lshl_or_b32 v16, s45, 5, v65
	v_lshlrev_b64 v[112:113], 7, v[16:17]
	v_lshl_add_u64 v[112:113], v[70:71], 0, v[112:113]
	global_load_dwordx4 v[46:49], v[112:113], off
	global_load_dwordx4 v[50:53], v[112:113], off offset:32
	global_load_dwordx4 v[54:57], v[112:113], off offset:64
	global_load_dwordx4 v[58:61], v[112:113], off offset:96
	s_cmp_eq_u32 s14, s44
	s_cselect_b64 s[0:1], -1, 0
	s_and_b64 s[0:1], s[0:1], vcc
	s_nop 7
	v_max_f32_e32 v0, v0, v0
	v_max_f32_e32 v0, 0, v0
	v_fma_f32 v16, v88, v0, 0
	v_max_f32_e32 v0, v1, v1
	v_max_f32_e32 v0, 0, v0
	v_fmac_f32_e32 v16, v89, v0
	v_max_f32_e32 v0, v2, v2
	v_max_f32_e32 v0, 0, v0
	v_fmac_f32_e32 v16, v90, v0
	v_max_f32_e32 v0, v3, v3
	v_max_f32_e32 v0, 0, v0
	v_fmac_f32_e32 v16, v91, v0
	v_max_f32_e32 v0, v4, v4
	v_max_f32_e32 v0, 0, v0
	v_fmac_f32_e32 v16, v92, v0
	v_max_f32_e32 v0, v5, v5
	v_max_f32_e32 v0, 0, v0
	v_fmac_f32_e32 v16, v93, v0
	v_max_f32_e32 v0, v6, v6
	v_max_f32_e32 v1, v7, v7
	v_max_f32_e32 v0, 0, v0
	v_max_f32_e32 v1, 0, v1
	v_pk_mul_f32 v[0:1], v[76:77], v[0:1]
	s_nop 0
	v_add_f32_e32 v0, v0, v16
	v_add_f32_e32 v2, v1, v0
	v_max_f32_e32 v0, v8, v8
	v_max_f32_e32 v1, v9, v9
	v_max_f32_e32 v0, 0, v0
	v_max_f32_e32 v1, 0, v1
	v_pk_mul_f32 v[0:1], v[78:79], v[0:1]
	s_nop 0
	v_add_f32_e32 v0, v0, v2
	v_add_f32_e32 v2, v1, v0
	v_max_f32_e32 v0, v10, v10
	v_max_f32_e32 v1, v11, v11
	v_max_f32_e32 v0, 0, v0
	v_max_f32_e32 v1, 0, v1
	v_pk_mul_f32 v[0:1], v[80:81], v[0:1]
	s_nop 0
	v_add_f32_e32 v0, v0, v2
	v_add_f32_e32 v2, v1, v0
	v_max_f32_e32 v0, v12, v12
	v_max_f32_e32 v1, v13, v13
	v_max_f32_e32 v0, 0, v0
	v_max_f32_e32 v1, 0, v1
	v_pk_mul_f32 v[0:1], v[82:83], v[0:1]
	s_nop 0
	v_add_f32_e32 v0, v0, v2
	v_add_f32_e32 v2, v1, v0
	v_max_f32_e32 v0, v14, v14
	v_max_f32_e32 v1, v15, v15
	v_max_f32_e32 v0, 0, v0
	v_max_f32_e32 v1, 0, v1
	v_pk_mul_f32 v[0:1], v[84:85], v[0:1]
	s_nop 0
	v_add_f32_e32 v0, v0, v2
	v_add_f32_e32 v0, v1, v0
	v_cndmask_b32_e64 v0, v0, v139, s[0:1]
	v_cmp_lt_i32_e64 s[0:1], -1, v0
	s_nop 1
	v_cndmask_b32_e64 v1, -1, v140, s[0:1]
	v_xor_b32_e32 v0, v1, v0
	ds_write_b32 v94, v0
	v_add_u32_e32 v94, 0x100, v94
	s_add_i32 s44, s44, 1
	s_cmp_eq_u32 s18, s44
	s_cbranch_scc1 .Lix1_done
; __device__ __forceinline__ unsigned ordkey(float f) { const unsigned u = __float_as_uint(f); return u ^ ((u >> 31) ? 0xFFFFFFFFu : 0x80000000u); }
; __device__ __forceinline__ void dsa_index_unit(const Ctx& c, int l, int b, int qb) {
;     ...
;         for (int kt = 0; kt <= qb; ++kt) {
;             bf16x8 Bn[4];
;             { const int kn = kt < qb ? kt + 1 : kt; const bf16* kp = KI + (size_t)(kn * 32 + n) * 64 + 8 * hf;
; #pragma unroll
;               for (int ks = 0; ks < 4; ++ks) Bn[ks] = *(const bf16x8*)(kp + 16 * ks); }
;             f32x16 acc;
; #pragma unroll
;             for (int v = 0; v < 16; ++v) acc[v] = 0.f;
; #pragma unroll
;             for (int ks = 0; ks < 4; ++ks) acc = __builtin_amdgcn_mfma_f32_32x32x16_bf16(Af[ks], Bc[ks], acc, 0, 0, 0);
;             float sc = 0.f;
; #pragma unroll
;             for (int v = 0; v < 16; ++v) sc += wq[v] * fmaxf(acc[v], 0.f);
;             if (kt == qb && n > (tq & 31)) sc = -INFINITY;
;             sk[kt * 64 + lane] = ordkey(sc);
; #pragma unroll
;             for (int ks = 0; ks < 4; ++ks) Bc[ks] = Bn[ks];
;         }
.Lix1_step1:
	s_waitcnt vmcnt(8)
	v_mfma_f32_32x32x16_bf16 v[0:15], v[18:21], v[96:99], 0
	v_mfma_f32_32x32x16_bf16 v[0:15], v[22:25], v[100:103], v[0:15]
	v_mfma_f32_32x32x16_bf16 v[0:15], v[26:29], v[104:107], v[0:15]
	v_mfma_f32_32x32x16_bf16 v[0:15], v[30:33], v[108:111], v[0:15]
	s_add_i32 s45, s44, 3
	s_min_u32 s45, s45, s14
	v_lshl_or_b32 v16, s45, 5, v65
	v_lshlrev_b64 v[112:113], 7, v[16:17]
	v_lshl_add_u64 v[112:113], v[70:71], 0, v[112:113]
	global_load_dwordx4 v[96:99], v[112:113], off
	global_load_dwordx4 v[100:103], v[112:113], off offset:32
	global_load_dwordx4 v[104:107], v[112:113], off offset:64
	global_load_dwordx4 v[108:111], v[112:113], off offset:96
	s_cmp_eq_u32 s14, s44
	s_cselect_b64 s[0:1], -1, 0
	s_and_b64 s[0:1], s[0:1], vcc
	s_nop 7
	v_max_f32_e32 v0, v0, v0
	v_max_f32_e32 v0, 0, v0
	v_fma_f32 v16, v88, v0, 0
	v_max_f32_e32 v0, v1, v1
	v_max_f32_e32 v0, 0, v0
	v_fmac_f32_e32 v16, v89, v0
	v_max_f32_e32 v0, v2, v2
	v_max_f32_e32 v0, 0, v0
	v_fmac_f32_e32 v16, v90, v0
	v_max_f32_e32 v0, v3, v3
	v_max_f32_e32 v0, 0, v0
	v_fmac_f32_e32 v16, v91, v0
	v_max_f32_e32 v0, v4, v4
	v_max_f32_e32 v0, 0, v0
	v_fmac_f32_e32 v16, v92, v0
	v_max_f32_e32 v0, v5, v5
	v_max_f32_e32 v0, 0, v0
	v_fmac_f32_e32 v16, v93, v0
	v_max_f32_e32 v0, v6, v6
	v_max_f32_e32 v1, v7, v7
	v_max_f32_e32 v0, 0, v0
	v_max_f32_e32 v1, 0, v1
	v_pk_mul_f32 v[0:1], v[76:77], v[0:1]
	s_nop 0
	v_add_f32_e32 v0, v0, v16
	v_add_f32_e32 v2, v1, v0
	v_max_f32_e32 v0, v8, v8
	v_max_f32_e32 v1, v9, v9
	v_max_f32_e32 v0, 0, v0
	v_max_f32_e32 v1, 0, v1
	v_pk_mul_f32 v[0:1], v[78:79], v[0:1]
	s_nop 0
	v_add_f32_e32 v0, v0, v2
	v_add_f32_e32 v2, v1, v0
	v_max_f32_e32 v0, v10, v10
	v_max_f32_e32 v1, v11, v11
	v_max_f32_e32 v0, 0, v0
	v_max_f32_e32 v1, 0, v1
	v_pk_mul_f32 v[0:1], v[80:81], v[0:1]
	s_nop 0
	v_add_f32_e32 v0, v0, v2
	v_add_f32_e32 v2, v1, v0
	v_max_f32_e32 v0, v12, v12
	v_max_f32_e32 v1, v13, v13
	v_max_f32_e32 v0, 0, v0
	v_max_f32_e32 v1, 0, v1
	v_pk_mul_f32 v[0:1], v[82:83], v[0:1]
	s_nop 0
	v_add_f32_e32 v0, v0, v2
	v_add_f32_e32 v2, v1, v0
	v_max_f32_e32 v0, v14, v14
	v_max_f32_e32 v1, v15, v15
	v_max_f32_e32 v0, 0, v0
	v_max_f32_e32 v1, 0, v1
	v_pk_mul_f32 v[0:1], v[84:85], v[0:1]
	s_nop 0
	v_add_f32_e32 v0, v0, v2
	v_add_f32_e32 v0, v1, v0
	v_cndmask_b32_e64 v0, v0, v139, s[0:1]
	v_cmp_lt_i32_e64 s[0:1], -1, v0
	s_nop 1
	v_cndmask_b32_e64 v1, -1, v140, s[0:1]
	v_xor_b32_e32 v0, v1, v0
	ds_write_b32 v94, v0
	v_add_u32_e32 v94, 0x100, v94
	s_add_i32 s44, s44, 1
	s_cmp_eq_u32 s18, s44
	s_cbranch_scc1 .Lix1_done
.Lix1_step2:
	s_waitcnt vmcnt(8)
	v_mfma_f32_32x32x16_bf16 v[0:15], v[18:21], v[164:167], 0
	v_mfma_f32_32x32x16_bf16 v[0:15], v[22:25], v[168:171], v[0:15]
	v_mfma_f32_32x32x16_bf16 v[0:15], v[26:29], v[172:175], v[0:15]
	v_mfma_f32_32x32x16_bf16 v[0:15], v[30:33], v[176:179], v[0:15]
	s_add_i32 s45, s44, 3
	s_min_u32 s45, s45, s14
	v_lshl_or_b32 v16, s45, 5, v65
	v_lshlrev_b64 v[112:113], 7, v[16:17]
	v_lshl_add_u64 v[112:113], v[70:71], 0, v[112:113]
	global_load_dwordx4 v[164:167], v[112:113], off
	global_load_dwordx4 v[168:171], v[112:113], off offset:32
	global_load_dwordx4 v[172:175], v[112:113], off offset:64
	global_load_dwordx4 v[176:179], v[112:113], off offset:96
	s_cmp_eq_u32 s14, s44
	s_cselect_b64 s[0:1], -1, 0
	s_and_b64 s[0:1], s[0:1], vcc
	s_nop 7
	v_max_f32_e32 v0, v0, v0
	v_max_f32_e32 v0, 0, v0
	v_fma_f32 v16, v88, v0, 0
	v_max_f32_e32 v0, v1, v1
	v_max_f32_e32 v0, 0, v0
	v_fmac_f32_e32 v16, v89, v0
	v_max_f32_e32 v0, v2, v2
	v_max_f32_e32 v0, 0, v0
	v_fmac_f32_e32 v16, v90, v0
	v_max_f32_e32 v0, v3, v3
	v_max_f32_e32 v0, 0, v0
	v_fmac_f32_e32 v16, v91, v0
	v_max_f32_e32 v0, v4, v4
	v_max_f32_e32 v0, 0, v0
	v_fmac_f32_e32 v16, v92, v0
	v_max_f32_e32 v0, v5, v5
	v_max_f32_e32 v0, 0, v0
	v_fmac_f32_e32 v16, v93, v0
	v_max_f32_e32 v0, v6, v6
	v_max_f32_e32 v1, v7, v7
	v_max_f32_e32 v0, 0, v0
	v_max_f32_e32 v1, 0, v1
	v_pk_mul_f32 v[0:1], v[76:77], v[0:1]
	s_nop 0
	v_add_f32_e32 v0, v0, v16
	v_add_f32_e32 v2, v1, v0
	v_max_f32_e32 v0, v8, v8
	v_max_f32_e32 v1, v9, v9
	v_max_f32_e32 v0, 0, v0
	v_max_f32_e32 v1, 0, v1
	v_pk_mul_f32 v[0:1], v[78:79], v[0:1]
	s_nop 0
	v_add_f32_e32 v0, v0, v2
	v_add_f32_e32 v2, v1, v0
	v_max_f32_e32 v0, v10, v10
	v_max_f32_e32 v1, v11, v11
	v_max_f32_e32 v0, 0, v0
	v_max_f32_e32 v1, 0, v1
	v_pk_mul_f32 v[0:1], v[80:81], v[0:1]
	s_nop 0
	v_add_f32_e32 v0, v0, v2
	v_add_f32_e32 v2, v1, v0
	v_max_f32_e32 v0, v12, v12
	v_max_f32_e32 v1, v13, v13
	v_max_f32_e32 v0, 0, v0
	v_max_f32_e32 v1, 0, v1
	v_pk_mul_f32 v[0:1], v[82:83], v[0:1]
	s_nop 0
	v_add_f32_e32 v0, v0, v2
	v_add_f32_e32 v2, v1, v0
	v_max_f32_e32 v0, v14, v14
	v_max_f32_e32 v1, v15, v15
	v_max_f32_e32 v0, 0, v0
	v_max_f32_e32 v1, 0, v1
	v_pk_mul_f32 v[0:1], v[84:85], v[0:1]
	s_nop 0
	v_add_f32_e32 v0, v0, v2
	v_add_f32_e32 v0, v1, v0
	v_cndmask_b32_e64 v0, v0, v139, s[0:1]
	v_cmp_lt_i32_e64 s[0:1], -1, v0
	s_nop 1
	v_cndmask_b32_e64 v1, -1, v140, s[0:1]
	v_xor_b32_e32 v0, v1, v0
	ds_write_b32 v94, v0
	v_add_u32_e32 v94, 0x100, v94
	s_add_i32 s44, s44, 1
	s_cmp_eq_u32 s18, s44
	s_cbranch_scc1 .Lix1_done
	s_branch .Lix1_step0
; __device__ __forceinline__ void dsa_index_unit(const Ctx& c, int l, int b, int qb) {
;     ...
;         unsigned key[64];
; #pragma unroll
;         for (int kt = 0; kt < 64; ++kt) { const unsigned kv = sk[kt * 64 + lane]; key[kt] = (kt <= qb) ? kv : 0u; }
.Lix1_done:
	s_waitcnt vmcnt(0)
	ds_read2st64_b32 v[8:9], v67 offset1:1
	ds_read2st64_b32 v[6:7], v67 offset0:2 offset1:3
	ds_read2st64_b32 v[4:5], v67 offset0:4 offset1:5
	ds_read2st64_b32 v[2:3], v67 offset0:6 offset1:7
	ds_read2st64_b32 v[0:1], v67 offset0:8 offset1:9
	ds_read2st64_b32 v[10:11], v67 offset0:10 offset1:11
	ds_read2st64_b32 v[102:103], v67 offset0:62 offset1:63
	v_readlane_b32 s0, v250, 22
	v_readlane_b32 s1, v250, 23
	s_mov_b32 s22, s11
	s_mov_b64 s[20:21], s[90:91]
	s_waitcnt lgkmcnt(2)
	v_cndmask_b32_e64 v101, v1, 0, s[0:1]
	v_readlane_b32 s0, v250, 16
	v_readlane_b32 s1, v250, 17
	s_waitcnt lgkmcnt(1)
	s_nop 0
	v_cndmask_b32_e64 v99, v10, 0, s[0:1]
	v_readlane_b32 s0, v250, 18
	v_readlane_b32 s1, v250, 19
	s_nop 1
	v_cndmask_b32_e64 v98, v11, 0, s[0:1]
	ds_read2st64_b32 v[10:11], v67 offset0:12 offset1:13
	v_readlane_b32 s0, v250, 26
	v_readlane_b32 s1, v250, 27
	s_waitcnt lgkmcnt(0)
	s_nop 0
	v_cndmask_b32_e64 v96, v10, 0, s[0:1]
	v_readlane_b32 s0, v250, 28
	v_readlane_b32 s1, v250, 29
	s_nop 1
	v_cndmask_b32_e64 v95, v11, 0, s[0:1]
	ds_read2st64_b32 v[10:11], v67 offset0:14 offset1:15
	v_readlane_b32 s0, v250, 30
	v_readlane_b32 s1, v250, 31
	s_waitcnt lgkmcnt(0)
	s_nop 0
	v_cndmask_b32_e64 v93, v10, 0, s[0:1]
	v_readlane_b32 s0, v250, 24
	v_readlane_b32 s1, v250, 25
	s_nop 1
	v_cndmask_b32_e64 v92, v11, 0, s[0:1]
	ds_read2st64_b32 v[10:11], v67 offset0:16 offset1:17
	v_readlane_b32 s0, v250, 40
	v_readlane_b32 s1, v250, 41
	s_waitcnt lgkmcnt(0)
	s_nop 0
	v_cndmask_b32_e64 v90, v10, 0, s[0:1]
	v_readlane_b32 s0, v250, 32
	v_readlane_b32 s1, v250, 33
	s_nop 1
	v_cndmask_b32_e64 v89, v11, 0, s[0:1]
	ds_read2st64_b32 v[10:11], v67 offset0:18 offset1:19
	v_readlane_b32 s0, v250, 10
	v_readlane_b32 s1, v250, 11
	s_waitcnt lgkmcnt(0)
	s_nop 0
	v_cndmask_b32_e64 v85, v10, 0, s[0:1]
	v_readlane_b32 s0, v250, 14
	v_readlane_b32 s1, v250, 15
	s_nop 1
	v_cndmask_b32_e64 v84, v11, 0, s[0:1]
	ds_read2st64_b32 v[10:11], v67 offset0:20 offset1:21
	v_readlane_b32 s0, v250, 34
	v_readlane_b32 s1, v250, 35
	s_waitcnt lgkmcnt(0)
	s_nop 0
	v_cndmask_b32_e64 v83, v10, 0, s[0:1]
	v_readlane_b32 s0, v250, 36
	v_readlane_b32 s1, v250, 37
	s_nop 1
	v_cndmask_b32_e64 v81, v11, 0, s[0:1]
	ds_read2st64_b32 v[10:11], v67 offset0:22 offset1:23
	v_readlane_b32 s0, v250, 38
	v_readlane_b32 s1, v250, 39
	s_waitcnt lgkmcnt(0)
	s_nop 0
	v_cndmask_b32_e64 v80, v10, 0, s[0:1]
	v_readlane_b32 s0, v252, 17
	v_readlane_b32 s1, v252, 18
	s_nop 1
	v_cndmask_b32_e64 v78, v11, 0, s[0:1]
	ds_read2st64_b32 v[10:11], v67 offset0:24 offset1:25
	v_readlane_b32 s0, v252, 19
	v_readlane_b32 s1, v252, 20
	s_waitcnt lgkmcnt(0)
	s_nop 0
	v_cndmask_b32_e64 v77, v10, 0, s[0:1]
	v_readlane_b32 s0, v252, 21
	v_readlane_b32 s1, v252, 22
	s_nop 1
	v_cndmask_b32_e64 v76, v11, 0, s[0:1]
	ds_read2st64_b32 v[10:11], v67 offset0:26 offset1:27
	v_readlane_b32 s0, v252, 23
	v_readlane_b32 s1, v252, 24
	s_waitcnt lgkmcnt(0)
	s_nop 0
	v_cndmask_b32_e64 v61, v10, 0, s[0:1]
	v_readlane_b32 s0, v252, 25
	v_readlane_b32 s1, v252, 26
	s_nop 1
	v_cndmask_b32_e64 v60, v11, 0, s[0:1]
	ds_read2st64_b32 v[10:11], v67 offset0:28 offset1:29
	v_readlane_b32 s0, v252, 27
	v_readlane_b32 s1, v252, 28
	s_waitcnt lgkmcnt(0)
	s_nop 0
	v_cndmask_b32_e64 v58, v10, 0, s[0:1]
	v_readlane_b32 s0, v252, 29
	v_readlane_b32 s1, v252, 30
	s_nop 1
	v_cndmask_b32_e64 v57, v11, 0, s[0:1]
	ds_read2st64_b32 v[10:11], v67 offset0:30 offset1:31
	v_readlane_b32 s0, v252, 31
	v_readlane_b32 s1, v252, 32
	s_waitcnt lgkmcnt(0)
	s_nop 0
	v_cndmask_b32_e64 v55, v10, 0, s[0:1]
	v_readlane_b32 s0, v252, 33
	v_readlane_b32 s1, v252, 34
	s_nop 1
	v_cndmask_b32_e64 v54, v11, 0, s[0:1]
	ds_read2st64_b32 v[10:11], v67 offset0:32 offset1:33
	v_readlane_b32 s0, v252, 35
	v_readlane_b32 s1, v252, 36
	s_waitcnt lgkmcnt(0)
	s_nop 0
	v_cndmask_b32_e64 v52, v10, 0, s[0:1]
	v_readlane_b32 s0, v252, 37
	v_readlane_b32 s1, v252, 38
	s_nop 1
	v_cndmask_b32_e64 v51, v11, 0, s[0:1]
	ds_read2st64_b32 v[10:11], v67 offset0:34 offset1:35
	v_readlane_b32 s0, v252, 39
	v_readlane_b32 s1, v252, 40
	s_waitcnt lgkmcnt(0)
; __device__ __forceinline__ void dsa_index_unit(const Ctx& c, int l, int b, int qb) {
;     ...
;         unsigned key[64];
; #pragma unroll
;         for (int kt = 0; kt < 64; ++kt) { const unsigned kv = sk[kt * 64 + lane]; key[kt] = (kt <= qb) ? kv : 0u; }
;         unsigned T = 0u;
; #pragma unroll 1
	s_nop 0
	v_cndmask_b32_e64 v49, v10, 0, s[0:1]
	v_readlane_b32 s0, v252, 41
	v_readlane_b32 s1, v252, 42
	s_nop 1
	v_cndmask_b32_e64 v48, v11, 0, s[0:1]
	ds_read2st64_b32 v[10:11], v67 offset0:36 offset1:37
	v_readlane_b32 s0, v252, 43
	v_readlane_b32 s1, v252, 44
	s_waitcnt lgkmcnt(0)
	s_nop 0
	v_cndmask_b32_e64 v46, v10, 0, s[0:1]
	v_readlane_b32 s0, v252, 45
	v_readlane_b32 s1, v252, 46
	s_nop 1
	v_cndmask_b32_e64 v45, v11, 0, s[0:1]
	ds_read2st64_b32 v[10:11], v67 offset0:38 offset1:39
	v_readlane_b32 s0, v252, 47
	v_readlane_b32 s1, v252, 48
	s_waitcnt lgkmcnt(0)
	s_nop 0
	v_cndmask_b32_e64 v43, v10, 0, s[0:1]
	v_readlane_b32 s0, v252, 49
	v_readlane_b32 s1, v252, 50
	s_nop 1
	v_cndmask_b32_e64 v42, v11, 0, s[0:1]
	ds_read2st64_b32 v[10:11], v67 offset0:40 offset1:41
	v_readlane_b32 s0, v252, 51
	v_readlane_b32 s1, v252, 52
	s_waitcnt lgkmcnt(0)
	s_nop 0
	v_cndmask_b32_e64 v40, v10, 0, s[0:1]
	v_readlane_b32 s0, v252, 53
	v_readlane_b32 s1, v252, 54
	s_nop 1
	v_cndmask_b32_e64 v39, v11, 0, s[0:1]
	ds_read2st64_b32 v[10:11], v67 offset0:42 offset1:43
	v_readlane_b32 s0, v252, 55
	v_readlane_b32 s1, v252, 56
	s_waitcnt lgkmcnt(0)
	s_nop 0
	v_cndmask_b32_e64 v38, v10, 0, s[0:1]
	v_readlane_b32 s0, v252, 57
	v_readlane_b32 s1, v252, 58
	s_nop 1
	v_cndmask_b32_e64 v36, v11, 0, s[0:1]
	ds_read2st64_b32 v[10:11], v67 offset0:44 offset1:45
	v_readlane_b32 s0, v252, 59
	v_readlane_b32 s1, v252, 60
	s_waitcnt lgkmcnt(0)
	s_nop 0
	v_cndmask_b32_e64 v35, v10, 0, s[0:1]
	v_readlane_b32 s0, v252, 61
	v_readlane_b32 s1, v252, 62
	s_nop 1
	v_cndmask_b32_e64 v33, v11, 0, s[0:1]
	ds_read2st64_b32 v[10:11], v67 offset0:46 offset1:47
	v_readlane_b32 s0, v252, 63
	v_readlane_b32 s1, v253, 0
	s_waitcnt lgkmcnt(0)
	s_nop 0
	v_cndmask_b32_e64 v32, v10, 0, s[0:1]
	v_readlane_b32 s0, v253, 1
	v_readlane_b32 s1, v253, 2
	s_nop 1
	v_cndmask_b32_e64 v30, v11, 0, s[0:1]
	ds_read2st64_b32 v[10:11], v67 offset0:48 offset1:49
	v_readlane_b32 s0, v253, 3
	v_readlane_b32 s1, v253, 4
	s_waitcnt lgkmcnt(0)
	s_nop 0
	v_cndmask_b32_e64 v29, v10, 0, s[0:1]
	v_readlane_b32 s0, v253, 5
	v_readlane_b32 s1, v253, 6
	s_nop 1
	v_cndmask_b32_e64 v27, v11, 0, s[0:1]
	ds_read2st64_b32 v[10:11], v67 offset0:50 offset1:51
	v_readlane_b32 s0, v253, 7
	v_readlane_b32 s1, v253, 8
	s_waitcnt lgkmcnt(0)
	s_nop 0
	v_cndmask_b32_e64 v26, v10, 0, s[0:1]
	v_readlane_b32 s0, v253, 9
	v_readlane_b32 s1, v253, 10
	s_nop 1
	v_cndmask_b32_e64 v24, v11, 0, s[0:1]
	ds_read2st64_b32 v[10:11], v67 offset0:52 offset1:53
	v_readlane_b32 s0, v253, 11
	v_readlane_b32 s1, v253, 12
	s_waitcnt lgkmcnt(0)
	s_nop 0
	v_cndmask_b32_e64 v22, v10, 0, s[0:1]
	v_readlane_b32 s0, v253, 13
	v_readlane_b32 s1, v253, 14
	s_nop 1
	v_cndmask_b32_e64 v21, v11, 0, s[0:1]
	ds_read2st64_b32 v[10:11], v67 offset0:54 offset1:55
	v_readlane_b32 s0, v253, 15
	v_readlane_b32 s1, v253, 16
	s_waitcnt lgkmcnt(0)
	s_nop 0
	v_cndmask_b32_e64 v20, v10, 0, s[0:1]
	v_readlane_b32 s0, v253, 17
	v_readlane_b32 s1, v253, 18
	s_nop 1
	v_cndmask_b32_e64 v19, v11, 0, s[0:1]
	ds_read2st64_b32 v[10:11], v67 offset0:56 offset1:57
	v_readlane_b32 s0, v253, 19
	v_readlane_b32 s1, v253, 20
	s_waitcnt lgkmcnt(0)
	s_nop 0
	v_cndmask_b32_e64 v18, v10, 0, s[0:1]
	v_readlane_b32 s0, v253, 21
	v_readlane_b32 s1, v253, 22
	s_nop 1
	v_cndmask_b32_e64 v16, v11, 0, s[0:1]
	ds_read2st64_b32 v[10:11], v67 offset0:58 offset1:59
	v_readlane_b32 s0, v253, 23
	v_readlane_b32 s1, v253, 24
	s_waitcnt lgkmcnt(0)
	s_nop 0
	v_cndmask_b32_e64 v15, v10, 0, s[0:1]
	v_readlane_b32 s0, v253, 25
	v_readlane_b32 s1, v253, 26
	s_nop 1
	v_cndmask_b32_e64 v14, v11, 0, s[0:1]
	ds_read2st64_b32 v[10:11], v67 offset0:60 offset1:61
	v_readlane_b32 s0, v253, 27
	v_readlane_b32 s1, v253, 28
	s_waitcnt lgkmcnt(0)
	s_nop 0
	v_cndmask_b32_e64 v13, v10, 0, s[0:1]
	v_readlane_b32 s0, v253, 29
	v_readlane_b32 s1, v253, 30
	v_mov_b32_e32 v10, 0
	s_nop 0
	v_cndmask_b32_e64 v12, v11, 0, s[0:1]
	v_readlane_b32 s0, v253, 31
	v_readlane_b32 s1, v253, 32
	s_nop 1
	v_cndmask_b32_e64 v11, v102, 0, s[0:1]
	v_readlane_b32 s0, v253, 33
	v_readlane_b32 s1, v253, 34
	s_nop 1
	v_cndmask_b32_e64 v1, 0, v103, s[0:1]
	s_mov_b32 s0, 31
